# cross attention shared K/V tiles double-buffered in LDS: one workgroup barrier per key step instead of two
# baseline (speedup 1.0000x reference)
; __device__ __forceinline__ void xattn_mfma_item(const bf16* qx, const bf16* kv, bf16* ox, LAS unsigned char* wl, int item, int lane) {
;     ...
;     const int trbase = (4 * hi + ((lane >> 2) & 3)) * PV128 + (16 * ((lane >> 4) & 1) + 4 * (lane & 3)) * 2;
;     const char* kvc = (const char*)(kv + (size_t)b * MEML * 1024);
;     const unsigned kfo = (unsigned)(r * 1024 + head * 128 + 8 * hi) * 2u;
;     const unsigned vlo = (unsigned)((lane >> 4) * 1024 + 512 + head * 128 + 8 * (lane & 15)) * 2u;
.LBB0_584:
	s_and_b64 vcc, exec, s[18:19]
	s_cbranch_vccz .LBB0_620
	s_add_u32 s2, s80, 0xac00000
	s_addc_u32 s3, s81, 0
	v_writelane_b32 v253, s2, 47
	v_and_b32_e32 v202, 63, v1
	s_nop 0
	v_writelane_b32 v253, s3, 48
	s_add_u32 s2, s80, 0xf000000
	s_addc_u32 s3, s81, 0
	v_writelane_b32 v253, s2, 49
	s_nop 1
	v_writelane_b32 v253, s3, 50
	s_ashr_i32 s2, s41, 6
	v_writelane_b32 v253, s2, 51
	s_cmp_gt_i32 s38, 1
	s_cbranch_scc0 .LBB0_596
	s_cmp_gt_i32 s38, 3
	s_mov_b64 s[2:3], -1
	s_cbranch_scc0 .LBB0_614
	v_readlane_b32 s2, v253, 10
	v_readlane_b32 s3, v253, 51
	s_add_i32 s10, s3, s2
	s_cmpk_gt_i32 s10, 0x7ff
	s_cbranch_scc1 .LBB0_613
	s_lshr_b32 s2, s10, 5
	s_lshl_b32 s2, s2, 3
	s_and_b32 s3, s10, 7
	s_add_i32 s2, s2, s3
	s_lshl_b32 s2, s2, 2
	s_bfe_u32 s3, s10, 0x20003
	s_or_b32 s10, s2, s3
	s_lshl_b64 s[2:3], s[78:79], 19
	s_and_b32 s2, s2, 0xffc00000
	s_lshl_b64 s[14:15], s[0:1], 22
	v_readlane_b32 s16, v253, 49
	v_readlane_b32 s17, v253, 50
	s_add_u32 s1, s16, s14
	s_addc_u32 s11, s17, s15
	v_readlane_b32 s15, v253, 51
	s_lshl_b32 s14, s15, 14
	s_add_i32 s14, s14, 0
	v_and_b32_e32 v5, 16, v1
	v_lshlrev_b32_e32 v6, 2, v202
	v_lshrrev_b32_e32 v2, 5, v202
	v_and_or_b32 v5, v6, 12, v5
	v_and_b32_e32 v6, 15, v1
	s_add_u32 s2, s12, s2
	v_lshlrev_b32_e32 v219, 3, v2
	v_lshlrev_b32_e32 v220, 2, v2
	v_lshrrev_b32_e32 v2, 2, v1
	v_lshrrev_b32_e32 v4, 4, v202
	v_lshlrev_b32_e32 v7, 3, v6
	s_addc_u32 s3, s13, s3
	v_and_or_b32 v2, v2, 3, v220
	v_lshl_or_b32 v222, v4, 10, v7
	v_mov_b32_e32 v7, s14
	s_movk_i32 s14, 0x110
	s_add_u32 s12, s62, s2
	v_mad_u32_u24 v4, v4, s14, v7
	v_mad_u32_u24 v2, v2, s14, v7
	s_addc_u32 s13, s63, s3
	s_lshl_b32 s14, s15, 7
	v_readlane_b32 s15, v253, 36
	s_lshl_b32 s14, s10, 7
	v_readlane_b32 s15, v253, 38
	v_and_b32_e32 v203, 31, v1
	v_lshlrev_b32_e32 v5, 1, v5
	v_lshlrev_b32_e32 v6, 4, v6
	s_add_u32 s15, s15, s2
	v_readlane_b32 s2, v253, 39
	v_lshl_or_b32 v221, v203, 10, v219
	s_addc_u32 s16, s2, s3
	v_add_u32_e32 v223, v4, v6
	v_add_u32_e32 v224, v2, v5
	v_readlane_b32 s21, v253, 51
	s_nop 3
	s_lshl_b32 s21, s21, 14
	v_subrev_u32_e32 v224, s21, v224
	v_xor_b32_e32 v224, 0x4000, v224
	s_branch .LBB0_590

; __device__ __forceinline__ void xattn_mfma_item(const bf16* qx, const bf16* kv, bf16* ox, LAS unsigned char* wl, int item, int lane) {
;     ...
;     { const char* qb_ = (const char*)qx; const unsigned qo = (unsigned)(token * DX + head * 128 + 8 * hi) * 2u;
; #pragma unroll
;       for (int d0 = 0; d0 < 8; ++d0) Qf[d0] = *(const s16x8*)(qb_ + qo + 32 * d0); }
;     f32x16 O[4];
; #pragma unroll
;     for (int k = 0; k < 4; ++k)
; #pragma unroll
;         for (int i = 0; i < 16; ++i) O[k][i] = 0.f;
;     float mrun = -1e30f, lsum = 0.f;
;     const int trbase = (4 * hi + ((lane >> 2) & 3)) * PV128 + (16 * ((lane >> 4) & 1) + 4 * (lane & 3)) * 2;
;     const char* kvc = (const char*)(kv + (size_t)b * MEML * 1024);
;     const unsigned kfo = (unsigned)(r * 1024 + head * 128 + 8 * hi) * 2u;
;     const unsigned vlo = (unsigned)((lane >> 4) * 1024 + 512 + head * 128 + 8 * (lane & 15)) * 2u;
;     s16x8 Kn[8]; v4u vn[8];
; #pragma unroll
;     for (int d0 = 0; d0 < 8; ++d0) Kn[d0] = *(const s16x8*)(kvc + kfo + 32 * d0);
; #pragma unroll
;     for (int i = 0; i < 8; ++i) vn[i] = *(const v4u*)(kvc + vlo + (size_t)(4 * i) * 2048);
.LBB0_590:
	s_and_b32 s2, s14, 0x180
	s_lshl_b32 s3, s10, 7
	v_add_lshl_u32 v2, v222, s2, 1
	v_add_lshl_u32 v4, v221, s2, 1
	s_lshl_b32 s2, s10, 3
	s_and_b32 s17, s3, 0x180
	s_bfe_i32 s3, s10, 0x1001c
	s_andn2_b32 s2, s2, 31
	s_lshr_b32 s3, s3, 21
	v_or_b32_e32 v6, s2, v203
	s_add_i32 s2, s2, s3
	v_lshl_or_b32 v225, v6, 9, s17
	s_ashr_i32 s2, s2, 11
	v_or_b32_e32 v6, v225, v219
	v_readlane_b32 s18, v253, 47
	s_ashr_i32 s3, s2, 31
	v_lshlrev_b32_e32 v6, 1, v6
	v_readlane_b32 s19, v253, 48
	s_lshl_b64 s[2:3], s[2:3], 19
	s_nop 3
	global_load_dwordx4 v[130:133], v6, s[18:19]
	global_load_dwordx4 v[126:129], v6, s[18:19] offset:32
	global_load_dwordx4 v[122:125], v6, s[18:19] offset:64
	global_load_dwordx4 v[118:121], v6, s[18:19] offset:96
	global_load_dwordx4 v[114:117], v6, s[18:19] offset:128
	global_load_dwordx4 v[110:113], v6, s[18:19] offset:160
	global_load_dwordx4 v[102:105], v6, s[18:19] offset:192
	global_load_dwordx4 v[98:101], v6, s[18:19] offset:224
	s_add_u32 s18, s1, s2
	v_or_b32_e32 v6, s17, v221
	s_addc_u32 s19, s11, s3
	v_lshlrev_b32_e32 v7, 1, v6
	v_or_b32_e32 v6, s17, v222
	v_lshlrev_b32_e32 v6, 1, v6
	v_readlane_b32 s21, v253, 51
	v_lshrrev_b32_e32 v234, 4, v202
	v_and_b32_e32 v235, 15, v202
	v_lshrrev_b32_e32 v238, 5, v202
	v_lshl_add_u32 v234, s21, 2, v234
	v_lshlrev_b32_e32 v235, 4, v235
	v_lshl_add_u32 v236, v234, 11, v235
	v_lshl_add_u32 v236, s17, 1, v236
	v_mov_b32_e32 v237, 0
	v_lshl_add_u64 v[232:233], s[18:19], 0, v[236:237]
	global_load_dwordx4 v[228:231], v[232:233], off
	global_load_dwordx4 v[240:243], v[232:233], off offset:1024
	v_mul_u32_u24_e32 v234, 0x110, v234
	v_add_u32_e32 v234, v234, v235
	v_xor_b32_e32 v239, 0x4000, v234
	v_add_u32_e32 v234, 0x8000, v234
	v_mul_u32_u24_e32 v235, 0x110, v203
	v_lshl_add_u32 v235, v238, 4, v235
	v_add_u32_e32 v235, 0x8000, v235
	v_mov_b32_e32 v7, v3
	v_lshl_add_u64 v[8:9], s[18:19], 0, v[6:7]
	v_add_co_u32_e32 v6, vcc, s83, v8
	s_movk_i32 s17, 0x6000
	s_nop 0
	v_addc_co_u32_e32 v7, vcc, 0, v9, vcc
	v_add_co_u32_e32 v6, vcc, s88, v8
	s_add_u32 s18, s12, s2
	s_nop 0
	v_addc_co_u32_e32 v7, vcc, 0, v9, vcc
	v_add_co_u32_e32 v6, vcc, s17, v8
	s_mov_b32 s17, 0x8000
	s_nop 0
	v_addc_co_u32_e32 v7, vcc, 0, v9, vcc
	v_add_co_u32_e32 v6, vcc, s17, v8
	s_mov_b32 s17, 0xa000
	s_nop 0
	v_addc_co_u32_e32 v7, vcc, 0, v9, vcc
	v_add_co_u32_e32 v6, vcc, s17, v8
	s_mov_b32 s17, 0xc000
	s_nop 0
	v_addc_co_u32_e32 v7, vcc, 0, v9, vcc
	v_add_co_u32_e32 v6, vcc, s17, v8
	s_mov_b32 s17, 0xe000
	s_nop 0
	v_addc_co_u32_e32 v7, vcc, 0, v9, vcc
	v_add_co_u32_e32 v6, vcc, s17, v8
	s_addc_u32 s19, s13, s3
	s_nop 0
	v_addc_co_u32_e32 v7, vcc, 0, v9, vcc
	s_add_u32 s2, s15, s2
	v_mov_b32_e32 v5, v3
	s_addc_u32 s3, s16, s3
	v_mov_b32_e32 v16, v3
	v_mov_b32_e32 v17, v3
	v_lshl_add_u64 v[204:205], s[18:19], 0, v[2:3]
	v_lshl_add_u64 v[206:207], s[2:3], 0, v[4:5]
	v_mov_b32_e32 v2, v3
	v_mov_b32_e32 v4, v3
	v_mov_b32_e32 v6, v3
	v_mov_b32_e32 v7, v3
	v_mov_b32_e32 v8, v3
	v_mov_b32_e32 v9, v3
	v_mov_b32_e32 v10, v3
	v_mov_b32_e32 v11, v3
	v_mov_b32_e32 v12, v3
	v_mov_b32_e32 v13, v3
	v_mov_b32_e32 v14, v3
	v_mov_b32_e32 v15, v3
	v_mov_b64_e32 v[32:33], v[16:17]
	v_mov_b64_e32 v[48:49], v[16:17]
	v_mov_b64_e32 v[64:65], v[16:17]
	v_mov_b64_e32 v[80:81], v[16:17]
	v_mov_b32_e32 v226, 0
	v_mov_b32_e32 v227, 0xf149f2ca
	s_mov_b64 s[2:3], 0
	v_mov_b64_e32 v[30:31], v[14:15]
	v_mov_b64_e32 v[28:29], v[12:13]
	v_mov_b64_e32 v[26:27], v[10:11]
	v_mov_b64_e32 v[24:25], v[8:9]
	v_mov_b64_e32 v[22:23], v[6:7]
	v_mov_b64_e32 v[20:21], v[4:5]
	v_mov_b64_e32 v[18:19], v[2:3]
	v_mov_b64_e32 v[46:47], v[14:15]
	v_mov_b64_e32 v[44:45], v[12:13]
	v_mov_b64_e32 v[42:43], v[10:11]
	v_mov_b64_e32 v[40:41], v[8:9]
	v_mov_b64_e32 v[38:39], v[6:7]
	v_mov_b64_e32 v[36:37], v[4:5]
	v_mov_b64_e32 v[34:35], v[2:3]
	v_mov_b64_e32 v[62:63], v[14:15]
	v_mov_b64_e32 v[60:61], v[12:13]
	v_mov_b64_e32 v[58:59], v[10:11]
	v_mov_b64_e32 v[56:57], v[8:9]
	v_mov_b64_e32 v[54:55], v[6:7]
	v_mov_b64_e32 v[52:53], v[4:5]
	v_mov_b64_e32 v[50:51], v[2:3]
	v_mov_b64_e32 v[78:79], v[14:15]
	v_mov_b64_e32 v[76:77], v[12:13]
	v_mov_b64_e32 v[74:75], v[10:11]
	v_mov_b64_e32 v[72:73], v[8:9]
	v_mov_b64_e32 v[70:71], v[6:7]
	v_mov_b64_e32 v[68:69], v[4:5]
	v_mov_b64_e32 v[66:67], v[2:3]
	s_waitcnt vmcnt(1)
	ds_write_b128 v234, v[228:231]
	s_waitcnt lgkmcnt(0)
	s_barrier
	ds_read_b128 v[158:161], v235
	ds_read_b128 v[154:157], v235 offset:32
	ds_read_b128 v[150:153], v235 offset:64
	ds_read_b128 v[146:149], v235 offset:96
	ds_read_b128 v[142:145], v235 offset:128
	ds_read_b128 v[138:141], v235 offset:160
	ds_read_b128 v[134:137], v235 offset:192
	ds_read_b128 v[106:109], v235 offset:224
	v_add_co_u32_e32 v232, vcc, 0x10000, v232
	s_nop 1
	v_addc_co_u32_e32 v233, vcc, 0, v233, vcc
	global_load_dwordx4 v[228:231], v[232:233], off
	s_branch .LBB0_592

; #define LAS __attribute__((address_space(3)))
; #define MFMA32(a, b, c) __builtin_amdgcn_mfma_f32_32x32x16_bf16(a, b, c, 0, 0, 0)
; __device__ __forceinline__ void xattn_mfma_item(const bf16* qx, const bf16* kv, bf16* ox, LAS unsigned char* wl, int item, int lane) {
;     ...
; #pragma unroll
;         for (int d0 = 0; d0 < 8; ++d0) Sx = MFMA32(Kn[d0], Qf[d0], Sx);
;         { LAS unsigned char* dst = wl + (lane >> 4) * PV128 + 16 * (lane & 15);
; #pragma unroll
;           for (int i = 0; i < 8; ++i) *(LAS v4u*)(dst + 4 * i * PV128) = vn[i]; }
;         if (jt < 7) { const char* tb = kvc + (size_t)((jt + 1) * 32) * 2048;
; #pragma unroll
;             for (int d0 = 0; d0 < 8; ++d0) Kn[d0] = *(const s16x8*)(tb + kfo + 32 * d0);
; #pragma unroll
;             for (int i = 0; i < 8; ++i) vn[i] = *(const v4u*)(tb + vlo + (size_t)(4 * i) * 2048); }
.LBB0_592:
	s_waitcnt lgkmcnt(0)
	v_mfma_f32_32x32x16_bf16 v[82:97], v[158:161], v[130:133], 0
	v_mfma_f32_32x32x16_bf16 v[82:97], v[154:157], v[126:129], v[82:97]
	v_mfma_f32_32x32x16_bf16 v[82:97], v[150:153], v[122:125], v[82:97]
	v_mfma_f32_32x32x16_bf16 v[82:97], v[146:149], v[118:121], v[82:97]
	v_mfma_f32_32x32x16_bf16 v[82:97], v[142:145], v[114:117], v[82:97]
	v_mfma_f32_32x32x16_bf16 v[82:97], v[138:141], v[110:113], v[82:97]
	v_mfma_f32_32x32x16_bf16 v[82:97], v[134:137], v[102:105], v[82:97]
	v_mfma_f32_32x32x16_bf16 v[82:97], v[106:109], v[98:101], v[82:97]
	v_xor_b32_e32 v234, 0x4000, v234
	v_xor_b32_e32 v235, 0x4000, v235
	v_xor_b32_e32 v239, 0x4000, v239
	v_xor_b32_e32 v224, 0x4000, v224
	s_waitcnt vmcnt(0)
	ds_write_b128 v234, v[228:231]
	ds_write_b128 v239, v[240:243]
	s_waitcnt lgkmcnt(0)
	s_barrier
	ds_read_b128 v[158:161], v235
	ds_read_b128 v[154:157], v235 offset:32
	ds_read_b128 v[150:153], v235 offset:64
	ds_read_b128 v[146:149], v235 offset:96
	ds_read_b128 v[142:145], v235 offset:128
	ds_read_b128 v[138:141], v235 offset:160
	ds_read_b128 v[134:137], v235 offset:192
	ds_read_b128 v[106:109], v235 offset:224
	global_load_dwordx4 v[240:243], v[232:233], off offset:1024
	s_cmp_gt_u32 s2, 0x50000
	s_cbranch_scc1 .Lxa_nopiece
	v_add_co_u32_e32 v232, vcc, 0x10000, v232
	s_nop 1
	v_addc_co_u32_e32 v233, vcc, 0, v233, vcc
	global_load_dwordx4 v[228:231], v[232:233], off

; #define LAS __attribute__((address_space(3)))
; #define MFMA32(a, b, c) __builtin_amdgcn_mfma_f32_32x32x16_bf16(a, b, c, 0, 0, 0)
; __device__ __forceinline__ float xh_max(float x) { auto rr = __builtin_amdgcn_permlane32_swap(__float_as_uint(x), __float_as_uint(x), false, false); return fmaxf(__uint_as_float(rr[0]), __uint_as_float(rr[1])); }
; __device__ __forceinline__ void xattn_mfma_item(const bf16* qx, const bf16* kv, bf16* ox, LAS unsigned char* wl, int item, int lane) {
;     ...
; #pragma unroll
;         for (int d0 = 0; d0 < 8; ++d0) Sx = MFMA32(Kn[d0], Qf[d0], Sx);
;         { LAS unsigned char* dst = wl + (lane >> 4) * PV128 + 16 * (lane & 15);
; #pragma unroll
;           for (int i = 0; i < 8; ++i) *(LAS v4u*)(dst + 4 * i * PV128) = vn[i]; }
;         if (jt < 7) { const char* tb = kvc + (size_t)((jt + 1) * 32) * 2048;
; #pragma unroll
;             for (int d0 = 0; d0 < 8; ++d0) Kn[d0] = *(const s16x8*)(tb + kfo + 32 * d0);
; #pragma unroll
;             for (int i = 0; i < 8; ++i) vn[i] = *(const v4u*)(tb + vlo + (size_t)(4 * i) * 2048); }
;         float P[16]; float tmax = -1e30f;
; #pragma unroll
;         for (int i = 0; i < 16; ++i) { P[i] = Sx[i] * SCX; tmax = fmaxf(tmax, P[i]); }
;         tmax = xh_max(tmax);
;         if (__any(tmax > mrun)) { const float mnew = fmaxf(mrun, tmax), alpha = __builtin_amdgcn_exp2f(mrun - mnew); lsum *= alpha; mrun = mnew;
.LBB0_594:
	s_waitcnt lgkmcnt(0)
	v_mfma_f32_32x32x16_bf16 v[82:97], v[158:161], v[130:133], 0
	s_mov_b32 s2, 0xf149f2ca
	v_mfma_f32_32x32x16_bf16 v[82:97], v[154:157], v[126:129], v[82:97]
	v_mfma_f32_32x32x16_bf16 v[82:97], v[150:153], v[122:125], v[82:97]
	v_mfma_f32_32x32x16_bf16 v[82:97], v[146:149], v[118:121], v[82:97]
	v_mfma_f32_32x32x16_bf16 v[82:97], v[142:145], v[114:117], v[82:97]
	v_mfma_f32_32x32x16_bf16 v[82:97], v[138:141], v[110:113], v[82:97]
	v_mfma_f32_32x32x16_bf16 v[82:97], v[134:137], v[102:105], v[82:97]
	v_mfma_f32_32x32x16_bf16 v[82:97], v[106:109], v[98:101], v[82:97]
	v_xor_b32_e32 v239, 0x4000, v239
	v_xor_b32_e32 v224, 0x4000, v224
	s_waitcnt vmcnt(0)
	ds_write_b128 v239, v[240:243]
	s_waitcnt lgkmcnt(0)
	s_barrier
	s_nop 11
	v_mul_f32_e32 v82, 0x3e0293ee, v82
	v_mul_f32_e32 v16, 0x3e0293ee, v83
	v_max3_f32 v2, v82, s2, v16
	v_mul_f32_e32 v17, 0x3e0293ee, v84
	v_mul_f32_e32 v15, 0x3e0293ee, v85
	v_max3_f32 v2, v2, v17, v15
	v_mul_f32_e32 v14, 0x3e0293ee, v86
	v_mul_f32_e32 v13, 0x3e0293ee, v87
	v_max3_f32 v2, v2, v14, v13
	v_mul_f32_e32 v12, 0x3e0293ee, v88
	v_mul_f32_e32 v11, 0x3e0293ee, v89
	v_max3_f32 v2, v2, v12, v11
	v_mul_f32_e32 v10, 0x3e0293ee, v90
	v_mul_f32_e32 v9, 0x3e0293ee, v91
	v_max3_f32 v2, v2, v10, v9
	v_mul_f32_e32 v8, 0x3e0293ee, v92
	v_mul_f32_e32 v7, 0x3e0293ee, v93
	v_max3_f32 v2, v2, v8, v7
	v_mul_f32_e32 v6, 0x3e0293ee, v94
	v_mul_f32_e32 v5, 0x3e0293ee, v95
	v_max3_f32 v83, v2, v6, v5
	v_mul_f32_e32 v4, 0x3e0293ee, v96
	v_mul_f32_e32 v2, 0x3e0293ee, v97
	v_max3_f32 v83, v83, v4, v2
	v_mov_b32_e32 v84, v83
	s_nop 1
	v_permlane32_swap_b32_e32 v83, v84
	v_max_f32_e32 v84, v84, v84
	v_max_f32_e32 v83, v83, v83
	v_max_f32_e32 v83, v83, v84
	v_cmp_gt_f32_e32 vcc, v83, v227
	s_cbranch_vccz .LBB0_589
	v_max_f32_e32 v83, v83, v83
	v_max_f32_e32 v84, v227, v227
	v_max_f32_e32 v83, v84, v83
	v_sub_f32_e32 v84, v227, v83
	v_exp_f32_e32 v84, v84
	v_mov_b32_e32 v227, v83
	v_pk_mul_f32 v[80:81], v[80:81], v[84:85] op_sel_hi:[1,0]
	v_pk_mul_f32 v[78:79], v[78:79], v[84:85] op_sel_hi:[1,0]
	v_pk_mul_f32 v[76:77], v[76:77], v[84:85] op_sel_hi:[1,0]
	v_pk_mul_f32 v[74:75], v[74:75], v[84:85] op_sel_hi:[1,0]
	v_pk_mul_f32 v[72:73], v[72:73], v[84:85] op_sel_hi:[1,0]
	v_pk_mul_f32 v[70:71], v[70:71], v[84:85] op_sel_hi:[1,0]
	v_pk_mul_f32 v[68:69], v[68:69], v[84:85] op_sel_hi:[1,0]
	v_pk_mul_f32 v[66:67], v[66:67], v[84:85] op_sel_hi:[1,0]
	v_pk_mul_f32 v[64:65], v[64:65], v[84:85] op_sel_hi:[1,0]
	v_pk_mul_f32 v[62:63], v[62:63], v[84:85] op_sel_hi:[1,0]
	v_pk_mul_f32 v[60:61], v[60:61], v[84:85] op_sel_hi:[1,0]
	v_pk_mul_f32 v[58:59], v[58:59], v[84:85] op_sel_hi:[1,0]
	v_pk_mul_f32 v[56:57], v[56:57], v[84:85] op_sel_hi:[1,0]
	v_pk_mul_f32 v[54:55], v[54:55], v[84:85] op_sel_hi:[1,0]
	v_pk_mul_f32 v[52:53], v[52:53], v[84:85] op_sel_hi:[1,0]
	v_pk_mul_f32 v[50:51], v[50:51], v[84:85] op_sel_hi:[1,0]
	v_pk_mul_f32 v[48:49], v[48:49], v[84:85] op_sel_hi:[1,0]
	v_pk_mul_f32 v[46:47], v[46:47], v[84:85] op_sel_hi:[1,0]
	v_pk_mul_f32 v[44:45], v[44:45], v[84:85] op_sel_hi:[1,0]
	v_pk_mul_f32 v[42:43], v[42:43], v[84:85] op_sel_hi:[1,0]
	v_pk_mul_f32 v[40:41], v[40:41], v[84:85] op_sel_hi:[1,0]
	v_pk_mul_f32 v[38:39], v[38:39], v[84:85] op_sel_hi:[1,0]
	v_pk_mul_f32 v[36:37], v[36:37], v[84:85] op_sel_hi:[1,0]
	v_pk_mul_f32 v[34:35], v[34:35], v[84:85] op_sel_hi:[1,0]
	v_pk_mul_f32 v[32:33], v[32:33], v[84:85] op_sel_hi:[1,0]
	v_pk_mul_f32 v[30:31], v[30:31], v[84:85] op_sel_hi:[1,0]
	v_pk_mul_f32 v[28:29], v[28:29], v[84:85] op_sel_hi:[1,0]
	v_pk_mul_f32 v[26:27], v[26:27], v[84:85] op_sel_hi:[1,0]
	v_pk_mul_f32 v[24:25], v[24:25], v[84:85] op_sel_hi:[1,0]
	v_pk_mul_f32 v[22:23], v[22:23], v[84:85] op_sel_hi:[1,0]
	v_pk_mul_f32 v[20:21], v[20:21], v[84:85] op_sel_hi:[1,0]
	v_pk_mul_f32 v[18:19], v[18:19], v[84:85] op_sel_hi:[1,0]
	v_mul_f32_e32 v226, v226, v84
	s_branch .LBB0_589
